# v sweep: slice-change gamma/beta reload without the vmcnt(0) drain (covered by the loop's counted waits), on top of the permlane reduction
# speedup vs baseline: 1.0060x; 1.0060x over previous
.LBB0_1139:
	s_and_b32 s39, s41, 31
	v_or_b32_e32 v138, s39, v74
	s_and_b32 s18, s6, 0xf80
	s_lshr_b32 s11, s41, 5
	s_cmp_lg_u32 s39, 0
	s_cbranch_scc1 .Lvsw_skip_gb
	v_readlane_b32 s100, v255, 10
	v_readlane_b32 s101, v255, 11
	v_readlane_b32 s98, v255, 12
	v_readlane_b32 s99, v255, 13
	v_lshl_or_b32 v250, s11, 7, v34
	v_lshlrev_b32_e32 v250, 2, v250
	s_nop 4
	global_load_dwordx2 v[246:247], v250, s[100:101]
	global_load_dwordx2 v[248:249], v250, s[98:99]
.Lvsw_skip_gb:
	v_readlane_b32 s100, v252, s39
	v_readlane_b32 s101, v253, s39
	v_ashrrev_i32_e32 v139, 31, v138
	v_lshl_add_u32 v173, s18, 1, v145
	s_lshl_b32 s18, s11, 7
	v_lshlrev_b64 v[138:139], 10, v[138:139]
	v_lshl_add_u64 v[138:139], v[138:139], 0, s[18:19]
	s_lshl_b32 s18, s11, 21
	s_waitcnt lgkmcnt(7)
	v_lshlrev_b32_sdwa v72, v141, v153 dst_sel:DWORD dst_unused:UNUSED_PAD src0_sel:DWORD src1_sel:WORD_0
	s_waitcnt vmcnt(7)
	v_cvt_pk_f32_fp8_e32 v[36:37], v28
	v_cvt_pk_f32_fp8_sdwa v[38:39], v28 src0_sel:WORD_1
	v_cvt_pk_f32_fp8_e32 v[40:41], v29
	v_cvt_pk_f32_fp8_sdwa v[28:29], v29 src0_sel:WORD_1
	v_cvt_pk_f32_fp8_e32 v[42:43], v30
	v_cvt_pk_f32_fp8_sdwa v[44:45], v30 src0_sel:WORD_1
	v_cvt_pk_f32_fp8_e32 v[48:49], v31
	v_cvt_pk_f32_fp8_sdwa v[50:51], v31 src0_sel:WORD_1
	v_lshl_add_u64 v[162:163], v[32:33], 0, s[18:19]
	s_waitcnt vmcnt(6)
	v_cvt_pk_f32_fp8_e32 v[30:31], v20
	v_cvt_pk_f32_fp8_sdwa v[46:47], v20 src0_sel:WORD_1
	v_cvt_pk_f32_fp8_e32 v[52:53], v21
	v_cvt_pk_f32_fp8_sdwa v[54:55], v21 src0_sel:WORD_1
	v_cvt_pk_f32_fp8_e32 v[58:59], v22
	v_cvt_pk_f32_fp8_sdwa v[60:61], v22 src0_sel:WORD_1
	v_cvt_pk_f32_fp8_e32 v[68:69], v23
	v_cvt_pk_f32_fp8_sdwa v[70:71], v23 src0_sel:WORD_1
	v_lshl_add_u32 v154, s39, 8, v77
	v_or_b32_e32 v138, v138, v34
	v_lshl_add_u64 v[156:157], v[162:163], 0, v[72:73]
	s_waitcnt lgkmcnt(6)
	v_lshlrev_b32_sdwa v72, v141, v146 dst_sel:DWORD dst_unused:UNUSED_PAD src0_sel:DWORD src1_sel:WORD_0
	s_waitcnt vmcnt(5)
	v_cvt_pk_f32_fp8_e32 v[20:21], v24
	v_cvt_pk_f32_fp8_sdwa v[22:23], v24 src0_sel:WORD_1
	v_cvt_pk_f32_fp8_e32 v[56:57], v25
	v_cvt_pk_f32_fp8_sdwa v[24:25], v25 src0_sel:WORD_1
	v_cvt_pk_f32_fp8_e32 v[62:63], v26
	v_cvt_pk_f32_fp8_sdwa v[64:65], v26 src0_sel:WORD_1
	v_cvt_pk_f32_fp8_e32 v[78:79], v27
	v_cvt_pk_f32_fp8_sdwa v[80:81], v27 src0_sel:WORD_1
	ds_read_u16 v175, v173
	ds_read_u16 v179, v173 offset:16
	ds_read_u16 v181, v173 offset:32
	ds_read_u16 v183, v173 offset:48
	ds_read_u16 v185, v173 offset:64
	ds_read_u16 v187, v173 offset:80
	ds_read_u16 v189, v173 offset:96
	ds_read_u16 v191, v173 offset:112
	ds_read_u16 v160, v154
	ds_read_u16 v161, v154 offset:16
	ds_read_u16 v169, v154 offset:32
	ds_read_u16 v174, v154 offset:48
	ds_read_u16 v180, v154 offset:64
	ds_read_u16 v182, v154 offset:80
	ds_read_u16 v184, v154 offset:96
	ds_read_u16 v186, v154 offset:112
	ds_read_u16 v153, v173 offset:128
	ds_read_u16 v188, v154 offset:128
	ds_read_u16 v190, v154 offset:144
	ds_read_u16 v192, v154 offset:160
	ds_read_u16 v193, v154 offset:176
	ds_read_u16 v195, v154 offset:192
	ds_read_u16 v197, v154 offset:208
	ds_read_u16 v199, v154 offset:224
	ds_read_u16 v201, v154 offset:240
	v_lshlrev_b64 v[154:155], 2, v[138:139]
	v_lshl_add_u64 v[138:139], v[138:139], 1, s[64:65]
	v_lshl_add_u64 v[158:159], v[162:163], 0, v[72:73]
	s_waitcnt lgkmcnt(14)
	v_lshlrev_b32_sdwa v72, v141, v151 dst_sel:DWORD dst_unused:UNUSED_PAD src0_sel:DWORD src1_sel:WORD_0
	s_waitcnt vmcnt(4)
	v_cvt_pk_f32_fp8_e32 v[26:27], v12
	v_cvt_pk_f32_fp8_sdwa v[66:67], v12 src0_sel:WORD_1
	v_cvt_pk_f32_fp8_e32 v[82:83], v13
	v_cvt_pk_f32_fp8_sdwa v[12:13], v13 src0_sel:WORD_1
	v_cvt_pk_f32_fp8_e32 v[86:87], v14
	v_cvt_pk_f32_fp8_sdwa v[88:89], v14 src0_sel:WORD_1
	v_cvt_pk_f32_fp8_e32 v[92:93], v15
	v_cvt_pk_f32_fp8_sdwa v[94:95], v15 src0_sel:WORD_1
	ds_read_u16 v146, v173 offset:144
	ds_read_u16 v151, v173 offset:160
	v_lshl_add_u64 v[166:167], s[62:63], 0, v[154:155]
	global_load_dword v203, v[138:139], off
	v_lshlrev_b32_e32 v168, 16, v160
	v_lshlrev_b32_e32 v170, 16, v161
	v_lshl_add_u64 v[138:139], s[60:61], 0, v[154:155]
	global_load_dwordx4 v[154:157], v[156:157], off
	s_nop 0
	global_load_dwordx4 v[158:161], v[158:159], off
	v_lshl_add_u64 v[204:205], v[162:163], 0, v[72:73]
	v_lshlrev_b32_sdwa v72, v141, v152 dst_sel:DWORD dst_unused:UNUSED_PAD src0_sel:DWORD src1_sel:WORD_0
	v_lshlrev_b32_e32 v172, 16, v169
	v_pk_fma_f32 v[36:37], v[36:37], v[168:169], 0 op_sel_hi:[1,0,0]
	v_pk_fma_f32 v[38:39], v[38:39], v[168:169], 0 op_sel_hi:[1,0,0]
	v_pk_fma_f32 v[40:41], v[40:41], v[168:169], 0 op_sel_hi:[1,0,0]
	v_pk_fma_f32 v[28:29], v[28:29], v[168:169], 0 op_sel_hi:[1,0,0]
	v_pk_fma_f32 v[42:43], v[42:43], v[168:169], 0 op_sel_hi:[1,0,0]
	v_pk_fma_f32 v[44:45], v[44:45], v[168:169], 0 op_sel_hi:[1,0,0]
	v_pk_fma_f32 v[48:49], v[48:49], v[168:169], 0 op_sel_hi:[1,0,0]
	v_pk_fma_f32 v[50:51], v[50:51], v[168:169], 0 op_sel_hi:[1,0,0]
	v_lshl_add_u64 v[168:169], v[162:163], 0, v[72:73]
	v_lshlrev_b32_sdwa v72, v141, v147 dst_sel:DWORD dst_unused:UNUSED_PAD src0_sel:DWORD src1_sel:WORD_0
	s_waitcnt vmcnt(6)
	v_cvt_pk_f32_fp8_e32 v[14:15], v16
	v_cvt_pk_f32_fp8_sdwa v[84:85], v16 src0_sel:WORD_1
	v_cvt_pk_f32_fp8_e32 v[90:91], v17
	v_cvt_pk_f32_fp8_sdwa v[16:17], v17 src0_sel:WORD_1
	v_cvt_pk_f32_fp8_e32 v[96:97], v18
	v_cvt_pk_f32_fp8_sdwa v[98:99], v18 src0_sel:WORD_1
	v_cvt_pk_f32_fp8_e32 v[100:101], v19
	v_cvt_pk_f32_fp8_sdwa v[18:19], v19 src0_sel:WORD_1
	ds_read_u16 v152, v173 offset:176
	ds_read_u16 v147, v173 offset:192
	global_load_dwordx2 v[166:167], v[166:167], off
	v_pk_fma_f32 v[30:31], v[30:31], v[170:171], v[36:37] op_sel_hi:[1,0,1]
	v_pk_fma_f32 v[46:47], v[46:47], v[170:171], v[38:39] op_sel_hi:[1,0,1]
	v_pk_fma_f32 v[52:53], v[52:53], v[170:171], v[40:41] op_sel_hi:[1,0,1]
	v_pk_fma_f32 v[28:29], v[54:55], v[170:171], v[28:29] op_sel_hi:[1,0,1]
	v_pk_fma_f32 v[54:55], v[58:59], v[170:171], v[42:43] op_sel_hi:[1,0,1]
	v_pk_fma_f32 v[44:45], v[60:61], v[170:171], v[44:45] op_sel_hi:[1,0,1]
	v_pk_fma_f32 v[48:49], v[68:69], v[170:171], v[48:49] op_sel_hi:[1,0,1]
	v_pk_fma_f32 v[50:51], v[70:71], v[170:171], v[50:51] op_sel_hi:[1,0,1]
	global_load_dwordx4 v[36:39], v[204:205], off
	global_load_dwordx4 v[40:43], v[168:169], off
	v_lshl_add_u64 v[58:59], v[162:163], 0, v[72:73]
	v_lshlrev_b32_sdwa v72, v141, v148 dst_sel:DWORD dst_unused:UNUSED_PAD src0_sel:DWORD src1_sel:WORD_0
	s_waitcnt lgkmcnt(14)
	v_lshlrev_b32_e32 v174, 16, v174
	v_pk_fma_f32 v[20:21], v[20:21], v[172:173], v[30:31] op_sel_hi:[1,0,1]
	v_pk_fma_f32 v[22:23], v[22:23], v[172:173], v[46:47] op_sel_hi:[1,0,1]
	v_pk_fma_f32 v[30:31], v[56:57], v[172:173], v[52:53] op_sel_hi:[1,0,1]
	v_pk_fma_f32 v[24:25], v[24:25], v[172:173], v[28:29] op_sel_hi:[1,0,1]
	v_pk_fma_f32 v[28:29], v[62:63], v[172:173], v[54:55] op_sel_hi:[1,0,1]
	v_pk_fma_f32 v[44:45], v[64:65], v[172:173], v[44:45] op_sel_hi:[1,0,1]
	v_pk_fma_f32 v[46:47], v[78:79], v[172:173], v[48:49] op_sel_hi:[1,0,1]
	v_pk_fma_f32 v[48:49], v[80:81], v[172:173], v[50:51] op_sel_hi:[1,0,1]
	v_lshl_add_u64 v[50:51], v[162:163], 0, v[72:73]
	ds_read_u16 v148, v173 offset:208
	v_lshlrev_b32_sdwa v72, v141, v149 dst_sel:DWORD dst_unused:UNUSED_PAD src0_sel:DWORD src1_sel:WORD_0
	ds_read_u16 v149, v173 offset:224
	v_pk_fma_f32 v[20:21], v[26:27], v[174:175], v[20:21] op_sel_hi:[1,0,1]
	v_pk_fma_f32 v[26:27], v[82:83], v[174:175], v[30:31] op_sel_hi:[1,0,1]
	v_pk_fma_f32 v[12:13], v[12:13], v[174:175], v[24:25] op_sel_hi:[1,0,1]
	v_pk_fma_f32 v[24:25], v[86:87], v[174:175], v[28:29] op_sel_hi:[1,0,1]
	v_pk_fma_f32 v[28:29], v[88:89], v[174:175], v[44:45] op_sel_hi:[1,0,1]
	v_pk_fma_f32 v[30:31], v[92:93], v[174:175], v[46:47] op_sel_hi:[1,0,1]
	v_pk_fma_f32 v[52:53], v[94:95], v[174:175], v[48:49] op_sel_hi:[1,0,1]
	global_load_dwordx4 v[44:47], v[58:59], off
	s_nop 0
	global_load_dwordx4 v[48:51], v[50:51], off
	v_lshlrev_b32_e32 v180, 16, v180
	v_lshl_add_u64 v[54:55], v[162:163], 0, v[72:73]
	v_lshlrev_b32_sdwa v72, v141, v150 dst_sel:DWORD dst_unused:UNUSED_PAD src0_sel:DWORD src1_sel:WORD_0
	ds_read_u16 v150, v173 offset:240
	v_pk_fma_f32 v[12:13], v[16:17], v[180:181], v[12:13] op_sel_hi:[1,0,1]
	v_pk_fma_f32 v[16:17], v[96:97], v[180:181], v[24:25] op_sel_hi:[1,0,1]
	v_pk_fma_f32 v[24:25], v[98:99], v[180:181], v[28:29] op_sel_hi:[1,0,1]
	v_pk_fma_f32 v[18:19], v[18:19], v[180:181], v[52:53] op_sel_hi:[1,0,1]
	v_lshl_add_u64 v[28:29], v[162:163], 0, v[72:73]
	global_load_dwordx4 v[52:55], v[54:55], off
	s_nop 0
	global_load_dwordx4 v[56:59], v[28:29], off
	s_waitcnt vmcnt(12)
	v_cvt_pk_f32_fp8_e32 v[102:103], v4
	v_cvt_pk_f32_fp8_sdwa v[104:105], v4 src0_sel:WORD_1
	v_cvt_pk_f32_fp8_e32 v[106:107], v5
	v_cvt_pk_f32_fp8_sdwa v[4:5], v5 src0_sel:WORD_1
	v_cvt_pk_f32_fp8_e32 v[108:109], v6
	v_cvt_pk_f32_fp8_sdwa v[110:111], v6 src0_sel:WORD_1
	v_cvt_pk_f32_fp8_e32 v[114:115], v7
	v_cvt_pk_f32_fp8_sdwa v[116:117], v7 src0_sel:WORD_1
	s_waitcnt vmcnt(11)
	v_cvt_pk_f32_fp8_e32 v[6:7], v8
	v_cvt_pk_f32_fp8_sdwa v[112:113], v8 src0_sel:WORD_1
	v_cvt_pk_f32_fp8_e32 v[118:119], v9
	v_cvt_pk_f32_fp8_sdwa v[8:9], v9 src0_sel:WORD_1
	v_cvt_pk_f32_fp8_e32 v[120:121], v10
	v_cvt_pk_f32_fp8_sdwa v[122:123], v10 src0_sel:WORD_1
	v_cvt_pk_f32_fp8_e32 v[124:125], v11
	v_cvt_pk_f32_fp8_sdwa v[10:11], v11 src0_sel:WORD_1
	s_waitcnt vmcnt(10)
	v_cvt_pk_f32_fp8_e32 v[126:127], v0
	v_cvt_pk_f32_fp8_sdwa v[128:129], v0 src0_sel:WORD_1
	v_cvt_pk_f32_fp8_e32 v[130:131], v1
	v_cvt_pk_f32_fp8_sdwa v[0:1], v1 src0_sel:WORD_1
	s_and_b32 s18, s3, 0xe00000
	v_pk_fma_f32 v[22:23], v[66:67], v[174:175], v[22:23] op_sel_hi:[1,0,1]
	v_cvt_pk_f32_fp8_e32 v[132:133], v2
	v_cvt_pk_f32_fp8_sdwa v[134:135], v2 src0_sel:WORD_1
	v_cvt_pk_f32_fp8_e32 v[136:137], v3
	v_cvt_pk_f32_fp8_sdwa v[2:3], v3 src0_sel:WORD_1
	v_lshl_add_u64 v[164:165], v[32:33], 0, s[18:19]
	v_lshlrev_b32_e32 v182, 16, v182
	v_pk_fma_f32 v[14:15], v[14:15], v[180:181], v[20:21] op_sel_hi:[1,0,1]
	v_pk_fma_f32 v[20:21], v[84:85], v[180:181], v[22:23] op_sel_hi:[1,0,1]
	v_pk_fma_f32 v[22:23], v[90:91], v[180:181], v[26:27] op_sel_hi:[1,0,1]
	v_pk_fma_f32 v[26:27], v[100:101], v[180:181], v[30:31] op_sel_hi:[1,0,1]
	v_lshlrev_b32_e32 v72, 7, v175
	v_lshlrev_b32_e32 v184, 16, v184
	v_pk_fma_f32 v[4:5], v[4:5], v[182:183], v[12:13] op_sel_hi:[1,0,1]
	v_pk_fma_f32 v[12:13], v[108:109], v[182:183], v[16:17] op_sel_hi:[1,0,1]
	v_pk_fma_f32 v[16:17], v[110:111], v[182:183], v[24:25] op_sel_hi:[1,0,1]
	v_pk_fma_f32 v[24:25], v[114:115], v[182:183], v[26:27] op_sel_hi:[1,0,1]
	v_pk_fma_f32 v[18:19], v[116:117], v[182:183], v[18:19] op_sel_hi:[1,0,1]
	v_lshl_add_u64 v[26:27], v[164:165], 0, v[72:73]
	v_lshlrev_b32_e32 v72, 7, v179
	s_waitcnt lgkmcnt(14)
	v_lshlrev_b32_e32 v186, 16, v186
	v_pk_fma_f32 v[4:5], v[8:9], v[184:185], v[4:5] op_sel_hi:[1,0,1]
	v_pk_fma_f32 v[10:11], v[10:11], v[184:185], v[18:19] op_sel_hi:[1,0,1]
	v_lshl_add_u64 v[18:19], v[164:165], 0, v[72:73]
	v_lshlrev_b32_e32 v72, 7, v181
	v_pk_fma_f32 v[14:15], v[102:103], v[182:183], v[14:15] op_sel_hi:[1,0,1]
	v_pk_fma_f32 v[20:21], v[104:105], v[182:183], v[20:21] op_sel_hi:[1,0,1]
	v_pk_fma_f32 v[22:23], v[106:107], v[182:183], v[22:23] op_sel_hi:[1,0,1]
	v_pk_fma_f32 v[66:67], v[0:1], v[186:187], v[4:5] op_sel_hi:[1,0,1]
	v_lshl_add_u64 v[0:1], v[164:165], 0, v[72:73]
	v_lshlrev_b32_e32 v72, 7, v183
	v_pk_fma_f32 v[6:7], v[6:7], v[184:185], v[14:15] op_sel_hi:[1,0,1]
	v_pk_fma_f32 v[14:15], v[112:113], v[184:185], v[20:21] op_sel_hi:[1,0,1]
	v_pk_fma_f32 v[20:21], v[118:119], v[184:185], v[22:23] op_sel_hi:[1,0,1]
	v_pk_fma_f32 v[8:9], v[120:121], v[184:185], v[12:13] op_sel_hi:[1,0,1]
	v_pk_fma_f32 v[12:13], v[122:123], v[184:185], v[16:17] op_sel_hi:[1,0,1]
	v_pk_fma_f32 v[80:81], v[2:3], v[186:187], v[10:11] op_sel_hi:[1,0,1]
	v_lshl_add_u64 v[2:3], v[164:165], 0, v[72:73]
	v_lshlrev_b32_e32 v72, 7, v185
	v_pk_fma_f32 v[16:17], v[124:125], v[184:185], v[24:25] op_sel_hi:[1,0,1]
	v_pk_fma_f32 v[62:63], v[128:129], v[186:187], v[14:15] op_sel_hi:[1,0,1]
	v_pk_fma_f32 v[64:65], v[130:131], v[186:187], v[20:21] op_sel_hi:[1,0,1]
	v_pk_fma_f32 v[70:71], v[134:135], v[186:187], v[12:13] op_sel_hi:[1,0,1]
	global_load_dwordx4 v[28:31], v[26:27], off
	global_load_dwordx4 v[20:23], v[18:19], off
	s_nop 0
	global_load_dwordx4 v[24:27], v[0:1], off
	global_load_dwordx4 v[12:15], v[2:3], off
	v_lshl_add_u64 v[0:1], v[164:165], 0, v[72:73]
	v_lshlrev_b32_e32 v72, 7, v187
	v_lshl_add_u64 v[2:3], v[164:165], 0, v[72:73]
	v_lshlrev_b32_e32 v72, 7, v189
	v_pk_fma_f32 v[60:61], v[126:127], v[186:187], v[6:7] op_sel_hi:[1,0,1]
	v_pk_fma_f32 v[78:79], v[136:137], v[186:187], v[16:17] op_sel_hi:[1,0,1]
	global_load_dwordx4 v[16:19], v[0:1], off
	global_load_dwordx4 v[4:7], v[2:3], off
	v_lshl_add_u64 v[0:1], v[164:165], 0, v[72:73]
	v_lshlrev_b32_e32 v72, 7, v191
	v_lshl_add_u64 v[2:3], v[164:165], 0, v[72:73]
	v_pk_fma_f32 v[68:69], v[132:133], v[186:187], v[8:9] op_sel_hi:[1,0,1]
	global_load_dwordx4 v[8:11], v[0:1], off
	s_nop 0
	global_load_dwordx4 v[0:3], v[2:3], off
	s_waitcnt vmcnt(16)
	v_cvt_pk_f32_fp8_e32 v[82:83], v154
	v_cvt_pk_f32_fp8_sdwa v[84:85], v154 src0_sel:WORD_1
	v_cvt_pk_f32_fp8_e32 v[86:87], v155
	v_cvt_pk_f32_fp8_sdwa v[88:89], v155 src0_sel:WORD_1
	v_cvt_pk_f32_fp8_e32 v[90:91], v156
	v_cvt_pk_f32_fp8_sdwa v[92:93], v156 src0_sel:WORD_1
	v_cvt_pk_f32_fp8_e32 v[94:95], v157
	v_cvt_pk_f32_fp8_sdwa v[96:97], v157 src0_sel:WORD_1
	s_waitcnt vmcnt(15)
	v_cvt_pk_f32_fp8_e32 v[100:101], v158
	v_cvt_pk_f32_fp8_sdwa v[102:103], v158 src0_sel:WORD_1
	v_cvt_pk_f32_fp8_e32 v[104:105], v159
	v_cvt_pk_f32_fp8_sdwa v[106:107], v159 src0_sel:WORD_1
	v_cvt_pk_f32_fp8_e32 v[108:109], v160
	v_cvt_pk_f32_fp8_sdwa v[110:111], v160 src0_sel:WORD_1
	v_cvt_pk_f32_fp8_e32 v[112:113], v161
	v_cvt_pk_f32_fp8_sdwa v[114:115], v161 src0_sel:WORD_1
	s_waitcnt vmcnt(13)
	v_cvt_pk_f32_fp8_e32 v[116:117], v36
	v_cvt_pk_f32_fp8_sdwa v[118:119], v36 src0_sel:WORD_1
	v_cvt_pk_f32_fp8_e32 v[120:121], v37
	v_cvt_pk_f32_fp8_sdwa v[36:37], v37 src0_sel:WORD_1
	v_cvt_pk_f32_fp8_e32 v[122:123], v38
	v_cvt_pk_f32_fp8_sdwa v[124:125], v38 src0_sel:WORD_1
	v_cvt_pk_f32_fp8_e32 v[126:127], v39
	v_cvt_pk_f32_fp8_sdwa v[38:39], v39 src0_sel:WORD_1
	v_lshlrev_b32_e32 v188, 16, v188
	s_waitcnt vmcnt(12)
	v_cvt_pk_f32_fp8_e32 v[128:129], v40
	v_cvt_pk_f32_fp8_sdwa v[130:131], v40 src0_sel:WORD_1
	v_cvt_pk_f32_fp8_e32 v[132:133], v41
	v_cvt_pk_f32_fp8_sdwa v[40:41], v41 src0_sel:WORD_1
	v_cvt_pk_f32_fp8_e32 v[134:135], v42
	v_cvt_pk_f32_fp8_sdwa v[136:137], v42 src0_sel:WORD_1
	v_cvt_pk_f32_fp8_e32 v[154:155], v43
	v_cvt_pk_f32_fp8_sdwa v[42:43], v43 src0_sel:WORD_1
	s_waitcnt lgkmcnt(13)
	v_lshlrev_b32_e32 v190, 16, v190
	v_pk_fma_f32 v[60:61], v[82:83], v[188:189], v[60:61] op_sel_hi:[1,0,1]
	v_pk_fma_f32 v[62:63], v[84:85], v[188:189], v[62:63] op_sel_hi:[1,0,1]
	v_pk_fma_f32 v[64:65], v[86:87], v[188:189], v[64:65] op_sel_hi:[1,0,1]
	v_pk_fma_f32 v[66:67], v[88:89], v[188:189], v[66:67] op_sel_hi:[1,0,1]
	v_pk_fma_f32 v[68:69], v[90:91], v[188:189], v[68:69] op_sel_hi:[1,0,1]
	v_pk_fma_f32 v[70:71], v[92:93], v[188:189], v[70:71] op_sel_hi:[1,0,1]
	v_pk_fma_f32 v[78:79], v[94:95], v[188:189], v[78:79] op_sel_hi:[1,0,1]
	v_pk_fma_f32 v[80:81], v[96:97], v[188:189], v[80:81] op_sel_hi:[1,0,1]
	s_waitcnt vmcnt(11)
	v_cvt_pk_f32_fp8_e32 v[82:83], v44
	v_cvt_pk_f32_fp8_sdwa v[84:85], v44 src0_sel:WORD_1
	v_cvt_pk_f32_fp8_e32 v[86:87], v45
	v_cvt_pk_f32_fp8_sdwa v[44:45], v45 src0_sel:WORD_1
	v_cvt_pk_f32_fp8_e32 v[88:89], v46
	v_cvt_pk_f32_fp8_sdwa v[90:91], v46 src0_sel:WORD_1
	v_cvt_pk_f32_fp8_e32 v[92:93], v47
	v_cvt_pk_f32_fp8_sdwa v[46:47], v47 src0_sel:WORD_1
	s_waitcnt lgkmcnt(12)
	v_lshlrev_b32_e32 v192, 16, v192
	v_pk_fma_f32 v[60:61], v[100:101], v[190:191], v[60:61] op_sel_hi:[1,0,1]
	v_pk_fma_f32 v[62:63], v[102:103], v[190:191], v[62:63] op_sel_hi:[1,0,1]
	v_pk_fma_f32 v[64:65], v[104:105], v[190:191], v[64:65] op_sel_hi:[1,0,1]
	v_pk_fma_f32 v[66:67], v[106:107], v[190:191], v[66:67] op_sel_hi:[1,0,1]
	v_pk_fma_f32 v[68:69], v[108:109], v[190:191], v[68:69] op_sel_hi:[1,0,1]
	v_pk_fma_f32 v[70:71], v[110:111], v[190:191], v[70:71] op_sel_hi:[1,0,1]
	v_pk_fma_f32 v[78:79], v[112:113], v[190:191], v[78:79] op_sel_hi:[1,0,1]
	v_pk_fma_f32 v[80:81], v[114:115], v[190:191], v[80:81] op_sel_hi:[1,0,1]
	s_waitcnt vmcnt(10)
	v_cvt_pk_f32_fp8_e32 v[94:95], v48
	v_cvt_pk_f32_fp8_sdwa v[96:97], v48 src0_sel:WORD_1
	v_cvt_pk_f32_fp8_e32 v[100:101], v49
	v_cvt_pk_f32_fp8_sdwa v[48:49], v49 src0_sel:WORD_1
	v_cvt_pk_f32_fp8_e32 v[102:103], v50
	v_cvt_pk_f32_fp8_sdwa v[104:105], v50 src0_sel:WORD_1
	v_cvt_pk_f32_fp8_e32 v[106:107], v51
	v_cvt_pk_f32_fp8_sdwa v[50:51], v51 src0_sel:WORD_1
	s_waitcnt lgkmcnt(11)
	v_lshlrev_b32_e32 v194, 16, v193
	v_pk_fma_f32 v[60:61], v[116:117], v[192:193], v[60:61] op_sel_hi:[1,0,1]
	v_pk_fma_f32 v[62:63], v[118:119], v[192:193], v[62:63] op_sel_hi:[1,0,1]
	v_pk_fma_f32 v[64:65], v[120:121], v[192:193], v[64:65] op_sel_hi:[1,0,1]
	v_pk_fma_f32 v[36:37], v[36:37], v[192:193], v[66:67] op_sel_hi:[1,0,1]
	v_pk_fma_f32 v[66:67], v[122:123], v[192:193], v[68:69] op_sel_hi:[1,0,1]
	v_pk_fma_f32 v[68:69], v[124:125], v[192:193], v[70:71] op_sel_hi:[1,0,1]
	v_pk_fma_f32 v[70:71], v[126:127], v[192:193], v[78:79] op_sel_hi:[1,0,1]
	v_pk_fma_f32 v[38:39], v[38:39], v[192:193], v[80:81] op_sel_hi:[1,0,1]
	s_waitcnt vmcnt(9)
	v_cvt_pk_f32_fp8_e32 v[78:79], v52
	v_cvt_pk_f32_fp8_sdwa v[80:81], v52 src0_sel:WORD_1
	v_cvt_pk_f32_fp8_e32 v[108:109], v53
	v_cvt_pk_f32_fp8_sdwa v[52:53], v53 src0_sel:WORD_1
	v_cvt_pk_f32_fp8_e32 v[110:111], v54
	v_cvt_pk_f32_fp8_sdwa v[112:113], v54 src0_sel:WORD_1
	v_cvt_pk_f32_fp8_e32 v[114:115], v55
	v_cvt_pk_f32_fp8_sdwa v[54:55], v55 src0_sel:WORD_1
	s_waitcnt lgkmcnt(10)
	v_lshlrev_b32_e32 v196, 16, v195
	v_pk_fma_f32 v[60:61], v[128:129], v[194:195], v[60:61] op_sel_hi:[1,0,1]
	v_pk_fma_f32 v[62:63], v[130:131], v[194:195], v[62:63] op_sel_hi:[1,0,1]
	v_pk_fma_f32 v[64:65], v[132:133], v[194:195], v[64:65] op_sel_hi:[1,0,1]
	v_pk_fma_f32 v[36:37], v[40:41], v[194:195], v[36:37] op_sel_hi:[1,0,1]
	v_pk_fma_f32 v[40:41], v[134:135], v[194:195], v[66:67] op_sel_hi:[1,0,1]
	v_pk_fma_f32 v[66:67], v[136:137], v[194:195], v[68:69] op_sel_hi:[1,0,1]
	v_pk_fma_f32 v[68:69], v[154:155], v[194:195], v[70:71] op_sel_hi:[1,0,1]
	v_pk_fma_f32 v[38:39], v[42:43], v[194:195], v[38:39] op_sel_hi:[1,0,1]
	s_waitcnt vmcnt(8)
	v_cvt_pk_f32_fp8_e32 v[42:43], v56
	v_cvt_pk_f32_fp8_sdwa v[70:71], v56 src0_sel:WORD_1
	v_cvt_pk_f32_fp8_e32 v[116:117], v57
	v_cvt_pk_f32_fp8_sdwa v[56:57], v57 src0_sel:WORD_1
	v_cvt_pk_f32_fp8_e32 v[118:119], v58
	v_cvt_pk_f32_fp8_sdwa v[120:121], v58 src0_sel:WORD_1
	v_cvt_pk_f32_fp8_e32 v[122:123], v59
	v_cvt_pk_f32_fp8_sdwa v[58:59], v59 src0_sel:WORD_1
	s_waitcnt lgkmcnt(9)
	v_lshlrev_b32_e32 v198, 16, v197
	v_pk_fma_f32 v[60:61], v[82:83], v[196:197], v[60:61] op_sel_hi:[1,0,1]
	v_pk_fma_f32 v[62:63], v[84:85], v[196:197], v[62:63] op_sel_hi:[1,0,1]
	v_pk_fma_f32 v[64:65], v[86:87], v[196:197], v[64:65] op_sel_hi:[1,0,1]
	v_pk_fma_f32 v[36:37], v[44:45], v[196:197], v[36:37] op_sel_hi:[1,0,1]
	v_pk_fma_f32 v[40:41], v[88:89], v[196:197], v[40:41] op_sel_hi:[1,0,1]
	v_pk_fma_f32 v[44:45], v[90:91], v[196:197], v[66:67] op_sel_hi:[1,0,1]
	v_pk_fma_f32 v[66:67], v[92:93], v[196:197], v[68:69] op_sel_hi:[1,0,1]
	v_pk_fma_f32 v[38:39], v[46:47], v[196:197], v[38:39] op_sel_hi:[1,0,1]
	s_waitcnt lgkmcnt(8)
	v_lshlrev_b32_e32 v200, 16, v199
	v_pk_fma_f32 v[46:47], v[94:95], v[198:199], v[60:61] op_sel_hi:[1,0,1]
	v_pk_fma_f32 v[60:61], v[96:97], v[198:199], v[62:63] op_sel_hi:[1,0,1]
	v_pk_fma_f32 v[62:63], v[100:101], v[198:199], v[64:65] op_sel_hi:[1,0,1]
	v_pk_fma_f32 v[36:37], v[48:49], v[198:199], v[36:37] op_sel_hi:[1,0,1]
	v_pk_fma_f32 v[40:41], v[102:103], v[198:199], v[40:41] op_sel_hi:[1,0,1]
	v_pk_fma_f32 v[44:45], v[104:105], v[198:199], v[44:45] op_sel_hi:[1,0,1]
	v_pk_fma_f32 v[48:49], v[106:107], v[198:199], v[66:67] op_sel_hi:[1,0,1]
	v_pk_fma_f32 v[38:39], v[50:51], v[198:199], v[38:39] op_sel_hi:[1,0,1]
	s_waitcnt lgkmcnt(7)
	v_lshlrev_b32_e32 v202, 16, v201
	v_pk_fma_f32 v[46:47], v[78:79], v[200:201], v[46:47] op_sel_hi:[1,0,1]
	v_pk_fma_f32 v[50:51], v[80:81], v[200:201], v[60:61] op_sel_hi:[1,0,1]
	v_pk_fma_f32 v[60:61], v[108:109], v[200:201], v[62:63] op_sel_hi:[1,0,1]
	v_pk_fma_f32 v[36:37], v[52:53], v[200:201], v[36:37] op_sel_hi:[1,0,1]
	v_pk_fma_f32 v[40:41], v[110:111], v[200:201], v[40:41] op_sel_hi:[1,0,1]
	v_pk_fma_f32 v[44:45], v[112:113], v[200:201], v[44:45] op_sel_hi:[1,0,1]
	v_pk_fma_f32 v[48:49], v[114:115], v[200:201], v[48:49] op_sel_hi:[1,0,1]
	v_pk_fma_f32 v[38:39], v[54:55], v[200:201], v[38:39] op_sel_hi:[1,0,1]
	v_pk_fma_f32 v[42:43], v[42:43], v[202:203], v[46:47] op_sel_hi:[1,0,1]
	v_pk_fma_f32 v[46:47], v[70:71], v[202:203], v[50:51] op_sel_hi:[1,0,1]
	v_pk_fma_f32 v[50:51], v[116:117], v[202:203], v[60:61] op_sel_hi:[1,0,1]
	v_pk_fma_f32 v[36:37], v[56:57], v[202:203], v[36:37] op_sel_hi:[1,0,1]
	v_pk_fma_f32 v[40:41], v[118:119], v[202:203], v[40:41] op_sel_hi:[1,0,1]
	v_pk_fma_f32 v[44:45], v[120:121], v[202:203], v[44:45] op_sel_hi:[1,0,1]
	v_pk_fma_f32 v[48:49], v[122:123], v[202:203], v[48:49] op_sel_hi:[1,0,1]
	v_pk_fma_f32 v[38:39], v[58:59], v[202:203], v[38:39] op_sel_hi:[1,0,1]
	s_nop 1
	v_permlane32_swap_b32 v42, v40
	v_permlane32_swap_b32 v43, v41
	v_permlane32_swap_b32 v46, v44
	v_permlane32_swap_b32 v47, v45
	v_permlane32_swap_b32 v50, v48
	v_permlane32_swap_b32 v51, v49
	v_permlane32_swap_b32 v36, v38
	v_permlane32_swap_b32 v37, v39
	s_add_i32 s7, s41, 1
	v_pk_add_f32 v[40:41], v[42:43], v[40:41]
	v_pk_add_f32 v[44:45], v[46:47], v[44:45]
	v_pk_add_f32 v[48:49], v[50:51], v[48:49]
	v_pk_add_f32 v[38:39], v[36:37], v[38:39]
	v_lshlrev_b32_e32 v98, 16, v203
	v_and_b32_e32 v99, 0xffff0000, v203
	s_addk_i32 s6, 0x80
	v_permlane16_swap_b32 v40, v48
	v_permlane16_swap_b32 v41, v49
	v_permlane16_swap_b32 v44, v38
	v_permlane16_swap_b32 v45, v39
	v_pk_add_f32 v[36:37], v[44:45], v[38:39]
	v_pk_add_f32 v[38:39], v[40:41], v[48:49]
	s_add_i32 s3, s3, 0x10000
	v_cndmask_b32_e64 v40, v38, v36, s[0:1]
	v_cndmask_b32_e64 v41, v39, v37, s[0:1]
	v_cndmask_b32_e64 v37, v37, v39, s[0:1]
	v_cndmask_b32_e64 v36, v36, v38, s[0:1]
	v_mov_b32_dpp v38, v40 row_ror:8 row_mask:0xf bank_mask:0xf bound_ctrl:1
	v_mov_b32_dpp v39, v41 row_ror:8 row_mask:0xf bank_mask:0xf bound_ctrl:1
	v_pk_add_f32 v[166:167], v[166:167], s[100:101] op_sel_hi:[1,0] neg_lo:[0,1] neg_hi:[0,1]
	s_nop 0
	v_pk_mul_f32 v[166:167], v[166:167], s[100:101] op_sel:[0,1]
	s_nop 0
	v_pk_fma_f32 v[166:167], v[246:247], v[166:167], v[248:249]
	s_nop 0
	v_pk_fma_f32 v[98:99], v[166:167], s[58:59], v[98:99] op_sel_hi:[1,0,1]
	v_pk_add_f32 v[36:37], v[36:37], v[38:39]
	s_mov_b32 s41, s7
	s_cmpk_eq_i32 s7, 0x100
	v_pk_add_f32 v[36:37], v[98:99], v[36:37]
	global_store_dwordx2 v[138:139], v[36:37], off
	s_cbranch_scc0 .LBB0_1139
	s_waitcnt vmcnt(0)
	s_barrier
	v_lshlrev_b64 v[0:1], 12, v[74:75]
	v_lshl_add_u64 v[0:1], s[60:61], 0, v[0:1]
	v_mov_b32_e32 v77, v73
	v_lshl_add_u64 v[64:65], v[0:1], 0, v[76:77]
	v_lshl_add_u64 v[66:67], s[90:91], 0, v[76:77]
	v_lshl_add_u64 v[68:69], s[68:69], 0, v[76:77]
	s_mov_b64 s[100:101], 0x1000
	v_lshl_add_u64 v[64:65], v[64:65], 0, s[100:101]
	global_load_dwordx4 v[206:209], v[66:67], off
	global_load_dwordx4 v[210:213], v[66:67], off offset:1024
	global_load_dwordx4 v[214:217], v[66:67], off offset:2048
	global_load_dwordx4 v[218:221], v[66:67], off offset:3072
	global_load_dwordx4 v[222:225], v[68:69], off
	global_load_dwordx4 v[226:229], v[68:69], off offset:1024
	global_load_dwordx4 v[230:233], v[68:69], off offset:2048
	global_load_dwordx4 v[234:237], v[68:69], off offset:3072
	global_load_dwordx4 v[0:3], v[64:65], off offset:-4096
	global_load_dwordx4 v[4:7], v[64:65], off offset:-3072
	global_load_dwordx4 v[8:11], v[64:65], off offset:-2048
	global_load_dwordx4 v[12:15], v[64:65], off offset:-1024
	global_load_dwordx4 v[40:43], v[66:67], off
	global_load_dwordx4 v[40:43], v[66:67], off
	global_load_dwordx4 v[40:43], v[66:67], off
	global_load_dwordx4 v[40:43], v[66:67], off
	s_mov_b32 s0, 0
